# asm-guide 7.11 on the A tile loop: slot/flag scalar work, LDS base adds and the back-edge branch moved in front of the per-tile barrier; K reads issue right after it
# speedup vs baseline: 1.0084x; 1.0084x over previous
; DI float max3f(float a, float b, float c) { float r; asm("v_max3_f32 %0, %1, %2, %3" : "=v"(r) : "v"(a), "v"(b), "v"(c)); return r; }
; DI float swapmax(float m) { auto rr = __builtin_amdgcn_permlane32_swap(__float_as_uint(m), __float_as_uint(m), false, false); return fmaxf(__uint_as_float(rr[0]), __uint_as_float(rr[1])); }
; #define SBAR() __builtin_amdgcn_sched_barrier(0)
; #define MF(a_, b_, c_) __builtin_amdgcn_mfma_f32_32x32x16_bf16(a_, b_, c_, 0, 0, 0)
; #define ATT_KLD(so_, h_) do { const lds_cptr kb_ = shm3 + (so_) + ((KIND == 0) ? m * 8192 : 0) + hi * 1024 + r32 * 16 + (h_) * 4096; \
;         kf[0] = *(const LAS bf16x8*)(kb_); kf[1] = *(const LAS bf16x8*)(kb_ + 512); kf[2] = *(const LAS bf16x8*)(kb_ + 2048); kf[3] = *(const LAS bf16x8*)(kb_ + 2560); } while (0)
; #define ATT_XLD(so_) do { if (KIND == 2) { const lds_cptr xb_ = shm3 + (so_) + 32768 + r32 * 16; x0 = *(const LAS bf16x8*)(xb_); x1 = *(const LAS bf16x8*)(xb_ + 512); if (hi) { x0 = (bf16x8){0, 0, 0, 0, 0, 0, 0, 0}; x1 = x0; } } } while (0)
; template <int KIND> DI void attn_unit(const Params& P, int b, int h, int qb, char* shm, float lam, bool dry = false) {
;     ...
;     f32x16 pa0, pa1, pb0, pb1;
;     bf16x8 kf[4], x0, x1;
;     ATT_KLD(0, 0); ATT_XLD(0);
;     pa0 = MF(kf[0], qr[0], negm); pa1 = MF(kf[1], qr[0], negm); pa0 = MF(kf[2], qr[1], pa0); pa1 = MF(kf[3], qr[1], pa1);
;     SBAR(); ATT_KLD(0, 1); SBAR();
;     pa0 = MF(kf[0], qr[2], pa0); pa1 = MF(kf[1], qr[2], pa1); pa0 = MF(kf[2], qr[3], pa0); pa1 = MF(kf[3], qr[3], pa1);
;     if (KIND == 2) { pa0 = MF(x0, ones, pa0); pa1 = MF(x1, ones, pa1); }
;     ATT_FIX(pa0, pa1, ATT_TILE(0));
;     { float rm = max3f(pa0[0], pa0[1], pa1[0]), rm2 = max3f(pa0[2], pa0[3], pa1[1]); rm = max3f(rm, pa1[2], pa1[3]);
; #pragma unroll
;       for (int r = 4; r < 16; r += 4) { rm = max3f(rm, pa0[r], pa0[r + 1]); rm2 = max3f(rm2, pa0[r + 2], pa0[r + 3]); rm = max3f(rm, pa1[r], pa1[r + 1]); rm2 = max3f(rm2, pa1[r + 2], pa1[r + 3]); }
;       rm = swapmax(max3f(rm, rm2, rm2)); ATT_DECIDE(pa0, pa1, rm); }
;     for (int i = 0; i < nt_eff; ++i) {
;         ATT_STEP_BAR(i);
;         const int sn = (sc == 3 * SLOT) ? 0 : sc + SLOT;
;         const lds_cptr vp = shm3 + sc + 16384 + vlane;
;         bf16x8 vq[4]; bf16x8 pw[4]; u32x4 w0, w1; float sacc = 0.f;
;     ...
;         ATT_KLD(sn, 0); ATT_XLD(sn);
.LBB0_399:
	s_cmp_lg_u32 0, -1
	v_lshlrev_b32_e32 v116, 2, v191
	s_cselect_b32 s15, 0, 0
	v_sub_u32_e32 v116, v192, v116
	s_lshl_b32 s19, s9, 7
	s_add_i32 s11, s11, s15
	v_subrev_u32_e32 v116, s19, v116
	s_lshl_b32 s3, s3, 9
	s_add_i32 s15, s11, 0x2000
	s_add_i32 s16, s11, 0x4000
	s_add_i32 s17, s11, 0x6000
	s_add_i32 s18, s6, 2
	s_addk_i32 s13, 0xfbc1
	v_subrev_u32_e32 v116, s3, v116
	s_add_i32 s3, 0, 0x232fc
	s_add_u32 s10, s29, s10
	s_addc_u32 s19, s38, 0
	s_add_u32 s0, s10, s0
	v_mov_b32_e32 v191, v2
	s_addc_u32 s1, s19, s1
	v_lshl_add_u64 v[184:185], s[0:1], 0, v[190:191]
	s_lshl_b32 s0, s12, 4
	s_and_b32 s0, s0, 0xc00
	s_add_u32 s0, s4, s0
	s_addc_u32 s1, s5, 0
	s_add_u32 s0, s39, s0
	s_addc_u32 s1, s40, s1
	v_lshlrev_b32_e32 v198, 3, v198
	s_mov_b32 s14, 0
	v_add_u32_e32 v192, s3, v116
	s_mov_b32 s3, 1
	v_lshl_add_u64 v[186:187], s[0:1], 0, v[190:191]
	s_mov_b32 s5, 0x8400
	s_movk_i32 s4, 0x80
	s_add_i32 s1, s3, 3
	s_cmp_lt_u32 s1, s18
	s_cselect_b32 s1, 1, 0
	s_add_i32 s0, s5, 0x8400
	s_cmp_lg_u32 s5, 0x18c00
	s_cselect_b32 s0, s0, 0
	v_add_u32_e32 v168, s0, v193
	v_add_u32_e32 v190, s5, v196
	s_cmp_ge_u32 s3, s6
	s_cbranch_scc1 .Lrot1_w0
	s_waitcnt vmcnt(4) lgkmcnt(0)
	s_branch .Lrot1_bar

; #define SBAR() __builtin_amdgcn_sched_barrier(0)
; #define MF(a_, b_, c_) __builtin_amdgcn_mfma_f32_32x32x16_bf16(a_, b_, c_, 0, 0, 0)
; #define ATT_KLD(so_, h_) do { const lds_cptr kb_ = shm3 + (so_) + ((KIND == 0) ? m * 8192 : 0) + hi * 1024 + r32 * 16 + (h_) * 4096; \
;         kf[0] = *(const LAS bf16x8*)(kb_); kf[1] = *(const LAS bf16x8*)(kb_ + 512); kf[2] = *(const LAS bf16x8*)(kb_ + 2048); kf[3] = *(const LAS bf16x8*)(kb_ + 2560); } while (0)
; #define ATT_XLD(so_) do { if (KIND == 2) { const lds_cptr xb_ = shm3 + (so_) + 32768 + r32 * 16; x0 = *(const LAS bf16x8*)(xb_); x1 = *(const LAS bf16x8*)(xb_ + 512); if (hi) { x0 = (bf16x8){0, 0, 0, 0, 0, 0, 0, 0}; x1 = x0; } } } while (0)
; #define G1(MFMA_, a_, W_, j_) do { MFMA_; pa0[a_] = EX(pa0[a_]); pa0[a_ + 1] = EX(pa0[a_ + 1]); sacc += pa0[a_]; sacc += pa0[a_ + 1]; W_[j_] = cvtpk(pa0[a_], pa0[a_ + 1]); PIN(pa0); PIN(sacc); PIN(W_); SBAR(); } while (0)
; template <int KIND> DI void attn_unit(const Params& P, int b, int h, int qb, char* shm, float lam, bool dry = false) {
;     ...
;         ATT_KLD(sn, 0); ATT_XLD(sn);
;         SBAR();
;     ...
;         G1(pb0 = MF(kf[0], qr[0], negm), 0, w0, 0);  G1(pb1 = MF(kf[1], qr[0], negm), 2, w0, 1);
;         G1(pb0 = MF(kf[2], qr[1], pb0), 4, w0, 2);   G1(pb1 = MF(kf[3], qr[1], pb1), 6, w0, 3);
.Lrot1_bar:
	s_barrier
	ds_read_b128 v[132:135], v168
	ds_read_b128 v[172:175], v168 offset:512
	ds_read_b128 v[176:179], v168 offset:2048
	ds_read_b128 v[180:183], v168 offset:2560
	s_waitcnt lgkmcnt(3)
	v_mfma_f32_32x32x16_bf16 v[116:131], v[132:135], v[160:163], v[4:19]
	v_exp_f32_e32 v100, v100
	v_exp_f32_e32 v101, v101
	v_add_f32_e32 v132, 0, v100
	v_add_f32_e32 v191, v101, v132
	v_cvt_pk_bf16_f32 v164, v100, v101
	s_waitcnt lgkmcnt(2)
	v_mfma_f32_32x32x16_bf16 v[132:147], v[172:175], v[160:163], v[4:19]
	s_cmp_eq_u32 s1, 0
	s_cbranch_scc1 .Lat1_nd0
	s_add_i32 m0, s11, s14
	s_nop 0
	global_load_lds_dwordx4 v[184:185], off

; DI float max3f(float a, float b, float c) { float r; asm("v_max3_f32 %0, %1, %2, %3" : "=v"(r) : "v"(a), "v"(b), "v"(c)); return r; }
; DI float swapmax(float m) { auto rr = __builtin_amdgcn_permlane32_swap(__float_as_uint(m), __float_as_uint(m), false, false); return fmaxf(__uint_as_float(rr[0]), __uint_as_float(rr[1])); }
; #define SBAR() __builtin_amdgcn_sched_barrier(0)
; #define MF(a_, b_, c_) __builtin_amdgcn_mfma_f32_32x32x16_bf16(a_, b_, c_, 0, 0, 0)
; #define ATT_KLD(so_, h_) do { const lds_cptr kb_ = shm3 + (so_) + ((KIND == 0) ? m * 8192 : 0) + hi * 1024 + r32 * 16 + (h_) * 4096; \
;         kf[0] = *(const LAS bf16x8*)(kb_); kf[1] = *(const LAS bf16x8*)(kb_ + 512); kf[2] = *(const LAS bf16x8*)(kb_ + 2048); kf[3] = *(const LAS bf16x8*)(kb_ + 2560); } while (0)
; #define ATT_XLD(so_) do { if (KIND == 2) { const lds_cptr xb_ = shm3 + (so_) + 32768 + r32 * 16; x0 = *(const LAS bf16x8*)(xb_); x1 = *(const LAS bf16x8*)(xb_ + 512); if (hi) { x0 = (bf16x8){0, 0, 0, 0, 0, 0, 0, 0}; x1 = x0; } } } while (0)
; template <int KIND> DI void attn_unit(const Params& P, int b, int h, int qb, char* shm, float lam, bool dry = false) {
;     ...
;     f32x16 pa0, pa1, pb0, pb1;
;     bf16x8 kf[4], x0, x1;
;     ATT_KLD(0, 0); ATT_XLD(0);
;     pa0 = MF(kf[0], qr[0], negm); pa1 = MF(kf[1], qr[0], negm); pa0 = MF(kf[2], qr[1], pa0); pa1 = MF(kf[3], qr[1], pa1);
;     SBAR(); ATT_KLD(0, 1); SBAR();
;     pa0 = MF(kf[0], qr[2], pa0); pa1 = MF(kf[1], qr[2], pa1); pa0 = MF(kf[2], qr[3], pa0); pa1 = MF(kf[3], qr[3], pa1);
;     if (KIND == 2) { pa0 = MF(x0, ones, pa0); pa1 = MF(x1, ones, pa1); }
;     ATT_FIX(pa0, pa1, ATT_TILE(0));
;     { float rm = max3f(pa0[0], pa0[1], pa1[0]), rm2 = max3f(pa0[2], pa0[3], pa1[1]); rm = max3f(rm, pa1[2], pa1[3]);
; #pragma unroll
;       for (int r = 4; r < 16; r += 4) { rm = max3f(rm, pa0[r], pa0[r + 1]); rm2 = max3f(rm2, pa0[r + 2], pa0[r + 3]); rm = max3f(rm, pa1[r], pa1[r + 1]); rm2 = max3f(rm2, pa1[r + 2], pa1[r + 3]); }
;       rm = swapmax(max3f(rm, rm2, rm2)); ATT_DECIDE(pa0, pa1, rm); }
;     for (int i = 0; i < nt_eff; ++i) {
;         ATT_STEP_BAR(i);
;         const int sn = (sc == 3 * SLOT) ? 0 : sc + SLOT;
;         const lds_cptr vp = shm3 + sc + 16384 + vlane;
;         bf16x8 vq[4]; bf16x8 pw[4]; u32x4 w0, w1; float sacc = 0.f;
;     ...
;         ATT_KLD(sn, 0); ATT_XLD(sn);
.LBB0_408:
	s_add_i32 s1, s14, 0x8400
	s_cmp_lg_u32 s14, 0x18c00
	s_cselect_b32 s14, s1, 0
	s_add_i32 s4, s4, 64
	v_add_u32_e32 v192, 0x100, v192
	v_lshl_add_u64 v[184:185], v[184:185], 0, s[62:63]
	s_cmp_eq_u32 s3, s18
	v_lshl_add_u64 v[186:187], v[186:187], 0, s[92:93]
	s_cbranch_scc1 .LBB0_412
	s_mov_b32 s5, s0
	s_add_i32 s1, s3, 3
	s_cmp_lt_u32 s1, s18
	s_cselect_b32 s1, 1, 0
	s_add_i32 s0, s5, 0x8400
	s_cmp_lg_u32 s5, 0x18c00
	s_cselect_b32 s0, s0, 0
	v_add_u32_e32 v168, s0, v193
	v_add_u32_e32 v190, s5, v196
	s_cmp_ge_u32 s3, s6
	s_cbranch_scc1 .Lrot2_w0
	s_waitcnt vmcnt(4) lgkmcnt(0)
	s_branch .Lrot2_bar

; #define SBAR() __builtin_amdgcn_sched_barrier(0)
; #define MF(a_, b_, c_) __builtin_amdgcn_mfma_f32_32x32x16_bf16(a_, b_, c_, 0, 0, 0)
; #define ATT_KLD(so_, h_) do { const lds_cptr kb_ = shm3 + (so_) + ((KIND == 0) ? m * 8192 : 0) + hi * 1024 + r32 * 16 + (h_) * 4096; \
;         kf[0] = *(const LAS bf16x8*)(kb_); kf[1] = *(const LAS bf16x8*)(kb_ + 512); kf[2] = *(const LAS bf16x8*)(kb_ + 2048); kf[3] = *(const LAS bf16x8*)(kb_ + 2560); } while (0)
; #define ATT_XLD(so_) do { if (KIND == 2) { const lds_cptr xb_ = shm3 + (so_) + 32768 + r32 * 16; x0 = *(const LAS bf16x8*)(xb_); x1 = *(const LAS bf16x8*)(xb_ + 512); if (hi) { x0 = (bf16x8){0, 0, 0, 0, 0, 0, 0, 0}; x1 = x0; } } } while (0)
; #define G1(MFMA_, a_, W_, j_) do { MFMA_; pa0[a_] = EX(pa0[a_]); pa0[a_ + 1] = EX(pa0[a_ + 1]); sacc += pa0[a_]; sacc += pa0[a_ + 1]; W_[j_] = cvtpk(pa0[a_], pa0[a_ + 1]); PIN(pa0); PIN(sacc); PIN(W_); SBAR(); } while (0)
; template <int KIND> DI void attn_unit(const Params& P, int b, int h, int qb, char* shm, float lam, bool dry = false) {
;     ...
;         ATT_KLD(sn, 0); ATT_XLD(sn);
;         SBAR();
;     ...
;         G1(pb0 = MF(kf[0], qr[0], negm), 0, w0, 0);  G1(pb1 = MF(kf[1], qr[0], negm), 2, w0, 1);
;         G1(pb0 = MF(kf[2], qr[1], pb0), 4, w0, 2);   G1(pb1 = MF(kf[3], qr[1], pb1), 6, w0, 3);
.Lrot2_bar:
	s_barrier
	ds_read_b128 v[84:87], v168
	ds_read_b128 v[172:175], v168 offset:512
	ds_read_b128 v[176:179], v168 offset:2048
	ds_read_b128 v[180:183], v168 offset:2560
	s_waitcnt lgkmcnt(3)
	v_mfma_f32_32x32x16_bf16 v[100:115], v[84:87], v[160:163], v[4:19]
	v_exp_f32_e32 v116, v116
	v_exp_f32_e32 v117, v117
	v_add_f32_e32 v84, 0, v116
	v_add_f32_e32 v191, v117, v84
	v_cvt_pk_bf16_f32 v164, v116, v117
	s_waitcnt lgkmcnt(2)
	v_mfma_f32_32x32x16_bf16 v[84:99], v[172:175], v[160:163], v[4:19]
	s_cmp_eq_u32 s1, 0
	s_cbranch_scc1 .Lat2_nd0
	s_add_i32 m0, s11, s14
	s_nop 0
	global_load_lds_dwordx4 v[184:185], off
